# dense: waves 0-3 ring DMA issued at top of their vector phase (tile t+2) + V-read interleave + P0 rewrite
# baseline (speedup 1.0000x reference)
; #define RESC(a) do { if (__any((a) < 1.f)) { if (hi == 0) al_l[r32] = (a); asm volatile("s_waitcnt lgkmcnt(0)" ::: "memory"); \
;     for (int d = 0; d < 4; ++d) for (int r = 0; r < 16; ++r) o[d][r] *= al_l[crow(r, hi)]; } } while (0)
; #define PSM(P0, P1, MN, AL, jt) do { if constexpr (DIL) { const int t_ = otid(), iq_ = (t_ >> 6) * QBLK + (t_ & 31), hi_ = (t_ >> 5) & 1; \
;       partialSM_dil(P0, P1, m_reg, MN, AL, (float)(-64 - iq_ + 4 * hi_ + 64 * (jt)), fmaxf(-64.f, (float)(-(i0 + iq_))), fminf(64.f, (float)(nsub - 1 - (i0 + iq_))), nslopeC); } \
;     else partialSM(P0, P1, m_reg, MN, AL); } while (0)
; #define PP_BAR(VM) do { if (VM) { asm volatile("s_waitcnt vmcnt(4) lgkmcnt(0)\n\ts_barrier" ::: "memory"); } else { asm volatile("s_waitcnt vmcnt(0) lgkmcnt(0)\n\ts_barrier" ::: "memory"); } } while (0)
; #define PP_BAR_PLAIN() asm volatile("s_waitcnt lgkmcnt(0)\n\ts_barrier" ::: "memory")
;     ...
;       if (grpB && t + 3 < NT) DMA(t + 3, (t + 3) & 3);
;     ...
;       partialSM_neg(pA0, pA1, m_reg, negm, alA, i0); if (!i0) RESC(alA);
;     ...
;       PSM(pA0, pA1, mnA, alA, t); RESC(alA);
;     ...
;       finishSM(pA0, pA1, alA, l_reg, pa0, pa1, pa2, pa3);
;     ...
;       { float dm_ = alA;
; #pragma unroll
;         for (int q_ = 0; q_ < 32; ++q_) asm volatile("v_add_f32 %0, %0, %0" : "+v"(dm_));
;         if (dm_ == 123.456f) l_reg += 1.f; }
;     ...
;       if (!(MK_PREB && t + 1 < NT)) { if (!grpB) PP_BAR(t + 2 < NT); else PP_BAR_PLAIN(); }
;       else if (!grpB) PP_BAR(t + 2 < NT);
;       if (!grpB && t + 3 < NT) DMA(t + 3, (t + 3) & 3);
.LBB0_56:
	v_cndmask_b32_e64 v66, 0, 1, s[82:83]
	v_cmp_ne_u32_e64 s[44:45], 1, v66
	s_cmp_lg_u64 s[0:1], 0
	s_cselect_b32 s15, 0x4000, 0
	s_sub_u32 s42, s86, s15
	s_subb_u32 s43, s87, 0
	v_lshl_add_u64 v[66:67], v[208:209], 0, s[42:43]
	s_mov_b64 s[40:41], 0xf00c000
	v_lshl_add_u64 v[184:185], v[66:67], 0, s[40:41]
	s_mov_b64 s[40:41], 0xf00c080
	v_lshl_add_u64 v[182:183], v[210:211], 0, s[42:43]
	v_lshl_add_u64 v[178:179], v[212:213], 0, s[42:43]
	v_lshl_add_u64 v[180:181], v[66:67], 0, s[40:41]
	s_cmp_lg_u32 s43, 0
	s_cbranch_scc1 .LBB0_58
	s_add_i32 s15, s42, 0xc000
	s_and_b32 s15, s15, 0xc000
	s_add_i32 s40, s13, s15
	s_mov_b32 m0, s40
	s_add_i32 s15, s14, s15
	global_load_lds_dwordx4 v[182:183], off
	s_mov_b32 m0, s15
	s_nop 0
	global_load_lds_dwordx4 v[184:185], off
	s_add_i32 m0, s40, 0x400
	s_nop 0
	global_load_lds_dwordx4 v[178:179], off
	s_add_i32 m0, s15, 0x400
	s_nop 0
	global_load_lds_dwordx4 v[180:181], off

; #define PK4(P, BASE, OUT) do { unsigned a0 = cvtpk(P[BASE + 0], P[BASE + 1]), a1 = cvtpk(P[BASE + 2], P[BASE + 3]);   \
;     unsigned b0 = cvtpk(P[BASE + 4], P[BASE + 5]), b1 = cvtpk(P[BASE + 6], P[BASE + 7]);                              \
;     u32x4 w = {a0, a1, b0, b1}; OUT = *reinterpret_cast<bf16x8*>(&w); } while (0)
; #define PP_BAR(VM) do { if (VM) { asm volatile("s_waitcnt vmcnt(4) lgkmcnt(0)\n\ts_barrier" ::: "memory"); } else { asm volatile("s_waitcnt vmcnt(0) lgkmcnt(0)\n\ts_barrier" ::: "memory"); } } while (0)
; #define PP_BAR_PLAIN() asm volatile("s_waitcnt lgkmcnt(0)\n\ts_barrier" ::: "memory")
; __device__ __forceinline__ void finishSM(f32x16& p0, f32x16& p1, float alpha, float& l_reg, bf16x8& pa0, bf16x8& pa1, bf16x8& pa2, bf16x8& pa3) {
;   for (int r = 0; r < 16; ++r) p1[r] = __builtin_amdgcn_exp2f(p1[r]);
;   float ps = 0; for (int r = 0; r < 16; ++r) ps += p0[r]; for (int r = 0; r < 16; ++r) ps += p1[r];
;   { auto rr = __builtin_amdgcn_permlane32_swap(__float_as_uint(ps), __float_as_uint(ps), false, false);
;     ps = __uint_as_float(rr[0]) + __uint_as_float(rr[1]); }
;   l_reg = l_reg * alpha + ps;
;     ...
;   PK4(p0, 0, pa0); PK4(p0, 8, pa1); PK4(p1, 0, pa2); PK4(p1, 8, pa3);
;     ...
;       if (!(MK_PREB && t + 1 < NT)) { if (!grpB) PP_BAR(t + 2 < NT); else PP_BAR_PLAIN(); }
;       else if (!grpB) PP_BAR(t + 2 < NT);
;       if (!grpB && t + 3 < NT) DMA(t + 3, (t + 3) & 3);
.LBB0_65:
	v_exp_f32_e32 v98, v98
	v_exp_f32_e32 v99, v99
	v_exp_f32_e32 v100, v100
	v_exp_f32_e32 v101, v101
	v_exp_f32_e32 v102, v102
	v_add_f32_e32 v162, 0, v98
	v_exp_f32_e32 v103, v103
	v_add_f32_e32 v162, v99, v162
	v_exp_f32_e32 v104, v104
	v_add_f32_e32 v162, v100, v162
	v_exp_f32_e32 v105, v105
	v_add_f32_e32 v162, v101, v162
	v_exp_f32_e32 v106, v106
	v_add_f32_e32 v162, v102, v162
	v_exp_f32_e32 v107, v107
	v_add_f32_e32 v162, v103, v162
	v_exp_f32_e32 v108, v108
	v_add_f32_e32 v162, v104, v162
	v_exp_f32_e32 v109, v109
	v_add_f32_e32 v162, v105, v162
	v_exp_f32_e32 v110, v110
	v_add_f32_e32 v162, v106, v162
	v_exp_f32_e32 v111, v111
	v_add_f32_e32 v162, v107, v162
	v_exp_f32_e32 v112, v112
	v_add_f32_e32 v162, v108, v162
	v_exp_f32_e32 v113, v113
	v_add_f32_e32 v162, v109, v162
	v_exp_f32_e32 v82, v82
	v_add_f32_e32 v162, v110, v162
	v_exp_f32_e32 v83, v83
	v_add_f32_e32 v162, v111, v162
	v_exp_f32_e32 v84, v84
	v_add_f32_e32 v162, v112, v162
	v_exp_f32_e32 v85, v85
	v_add_f32_e32 v162, v113, v162
	v_exp_f32_e32 v86, v86
	v_add_f32_e32 v162, v82, v162
	v_exp_f32_e32 v87, v87
	v_add_f32_e32 v162, v83, v162
	v_exp_f32_e32 v88, v88
	v_add_f32_e32 v162, v84, v162
	v_exp_f32_e32 v89, v89
	v_add_f32_e32 v162, v85, v162
	v_exp_f32_e32 v90, v90
	v_add_f32_e32 v162, v86, v162
	v_exp_f32_e32 v91, v91
	v_add_f32_e32 v162, v87, v162
	v_exp_f32_e32 v92, v92
	v_add_f32_e32 v162, v88, v162
	v_exp_f32_e32 v93, v93
	v_add_f32_e32 v162, v89, v162
	v_exp_f32_e32 v94, v94
	v_add_f32_e32 v162, v90, v162
	v_exp_f32_e32 v95, v95
	v_add_f32_e32 v162, v91, v162
	v_exp_f32_e32 v96, v96
	v_add_f32_e32 v162, v92, v162
	v_exp_f32_e32 v97, v97
	v_add_f32_e32 v162, v93, v162
	v_add_f32_e32 v162, v94, v162
	v_add_f32_e32 v162, v95, v162
	v_add_f32_e32 v162, v96, v162
	v_add_f32_e32 v243, v97, v162
	v_mov_b32_e32 v245, v243
	v_cvt_pk_bf16_f32 v166, v82, v83
	v_cndmask_b32_e64 v82, 0, 1, s[0:1]
	s_nop 0
	v_permlane32_swap_b32_e32 v243, v245
	v_cmp_ne_u32_e64 s[42:43], 1, v82
	s_andn2_b64 vcc, exec, s[0:1]
	v_cvt_pk_bf16_f32 v174, v98, v99
	v_cvt_pk_bf16_f32 v175, v100, v101
	v_cvt_pk_bf16_f32 v176, v102, v103
	v_cvt_pk_bf16_f32 v177, v104, v105
	v_cvt_pk_bf16_f32 v170, v106, v107
	v_cvt_pk_bf16_f32 v171, v108, v109
	v_cvt_pk_bf16_f32 v172, v110, v111
	v_cvt_pk_bf16_f32 v173, v112, v113
	v_cvt_pk_bf16_f32 v167, v84, v85
	v_cvt_pk_bf16_f32 v168, v86, v87
	v_cvt_pk_bf16_f32 v169, v88, v89
	v_cvt_pk_bf16_f32 v162, v90, v91
	v_cvt_pk_bf16_f32 v163, v92, v93
	v_cvt_pk_bf16_f32 v164, v94, v95
	v_cvt_pk_bf16_f32 v165, v96, v97
	s_cbranch_vccnz .LBB0_67
	s_waitcnt vmcnt(4) lgkmcnt(0)
	s_barrier
	s_cmp_lg_u32 s86, 0x1f0000
	s_cbranch_scc1 .LBB0_67
	s_mov_b64 s[84:85], 0x4000
	v_lshl_add_u64 v[182:183], v[182:183], 0, s[84:85]
	v_lshl_add_u64 v[184:185], v[184:185], 0, s[84:85]
	v_lshl_add_u64 v[178:179], v[178:179], 0, s[84:85]
	v_lshl_add_u64 v[180:181], v[180:181], 0, s[84:85]
	s_add_i32 s15, s86, 0xc000
	s_and_b32 s15, s15, 0xc000
	s_add_i32 s84, s13, s15
	s_mov_b32 m0, s84
	s_add_i32 s15, s14, s15
	global_load_lds_dwordx4 v[182:183], off
	s_mov_b32 m0, s15
	s_nop 0
	global_load_lds_dwordx4 v[184:185], off
	s_add_i32 m0, s84, 0x400
	s_nop 0
	global_load_lds_dwordx4 v[178:179], off
	s_add_i32 m0, s15, 0x400
	s_nop 0
	global_load_lds_dwordx4 v[180:181], off
